# P4 small intra-XCD stagger (4 workgroup groups, 0..3 x s_sleep 50 at phase start) to desynchronise epilogue store bursts, on top of P1 LDS tables + P2 pointer SALU
# speedup vs baseline: 1.0031x; 1.0031x over previous
; __global__ void __launch_bounds__(NWAVES * 64, 2) mega_fwd(Args args) {
;     ...
;         { const int rowi = F.tid & 255;
;           for (int i = F.tid >> 8; i < pg8::UP_TAB_ROUNDS; i += 2) { const int pm = S.pm_at(i); if (pm < 0) break;
;               const f32x4* p = (const f32x4*)(F.stats + (size_t)(pm * 256 + rowi) * 16); const f32x4 a = p[0], b = p[1], c = p[2], d = p[3];
;               const float ssum = ((a[0] + a[1]) + (a[2] + a[3])) + ((b[0] + b[1]) + (b[2] + b[3])) + ((c[0] + c[1]) + (c[2] + c[3])) + ((d[0] + d[1]) + (d[2] + d[3]));
;               tab[i * 256 + rowi] = __builtin_amdgcn_rsqf(ssum * (1.0f / 1024.0f) + EPS); }
;           __syncthreads(); }
;         pg8::EpiUp E{F.H, F.stats, tab};
;         pg8::gemm_phase<pg8::EpiUp, pg8::StaticOrder, PG8_ALIGN, PG8_SP2>(F.lds + RING_OFF, g, S, E);
.LBB0_1367:
	s_or_b64 exec, exec, s[6:7]
	s_cmp_gt_i32 s30, 0
	s_cselect_b64 s[0:1], -1, 0
	s_cmpk_lt_i32 s2, 0xc00
	s_cselect_b64 s[4:5], -1, 0
	s_and_b64 s[0:1], s[4:5], s[0:1]
	v_cndmask_b32_e64 v1, 0, 1, s[0:1]
	v_cmp_ne_u32_e64 s[4:5], 1, v1
	s_andn2_b64 vcc, exec, s[0:1]
	v_readfirstlane_b32 s12, v208
	s_waitcnt lgkmcnt(0)
	s_barrier
	s_lshr_b32 s98, s2, 3
	s_and_b32 s98, s98, 3
	s_cbranch_scc0 .Lstg_p4_done
